# GEMM K-loop: one static s_setprio 1 for waves 4-7 (stagger half), per-phase flips removed
# baseline (speedup 1.0000x reference)
.LBB0_741:
	s_and_b64 vcc, exec, s[4:5]
	s_cbranch_vccz .LBB0_813
	s_ashr_i32 s21, s20, 31
	s_lshl_b64 s[92:93], s[20:21], 9
	s_ashr_i32 s4, s2, 31
	s_mul_i32 s4, s92, s4
	s_mul_hi_u32 s5, s92, s2
	s_add_i32 s9, s5, s4
	s_lshr_b64 s[4:5], s[20:21], 23
	s_ashr_i32 s19, s18, 31
	s_mul_i32 s4, s4, s2
	s_lshl_b64 s[94:95], s[18:19], 9
	s_add_i32 s9, s9, s4
	s_ashr_i32 s4, s85, 31
	v_lshlrev_b32_e32 v0, 5, v0
	s_mul_i32 s4, s94, s4
	s_mul_hi_u32 s5, s94, s85
	v_and_b32_e32 v18, 32, v0
	v_mul_i32_i24_e32 v0, 64, v3
	s_add_i32 s12, s5, s4
	s_lshr_b64 s[4:5], s[18:19], 23
	v_lshlrev_b32_e32 v5, 5, v5
	s_ashr_i32 s8, s49, 6
	v_sub_u32_e32 v0, v1, v0
	s_mul_i32 s4, s4, s85
	v_and_b32_e32 v15, 32, v5
	v_lshlrev_b32_e32 v5, 6, v8
	s_ashr_i32 s7, s49, 8
	s_lshl_b64 s[22:23], s[20:21], 8
	s_lshl_b64 s[90:91], s[18:19], 8
	s_lshl_b32 s53, s8, 10
	v_ashrrev_i16_sdwa v0, v228, sext(v0) dst_sel:DWORD dst_unused:UNUSED_PAD src0_sel:DWORD src1_sel:BYTE_0
	s_add_i32 s12, s12, s4
	s_mul_i32 s4, s94, s85
	v_sub_u32_e32 v5, v6, v5
	v_bfe_i32 v19, v0, 0, 16
	s_add_u32 s4, s16, s4
	v_ashrrev_i16_sdwa v5, v228, sext(v5) dst_sel:DWORD dst_unused:UNUSED_PAD src0_sel:DWORD src1_sel:BYTE_0
	v_add_u32_e32 v0, v18, v19
	v_mul_lo_u32 v20, v2, s20
	v_mul_lo_u32 v1, v4, s18
	s_addc_u32 s5, s17, s12
	s_add_i32 s19, s53, 0
	v_bfe_i32 v16, v5, 0, 16
	v_add_lshl_u32 v178, v0, v20, 1
	v_add_lshl_u32 v180, v1, v0, 1
	v_mov_b32_e32 v0, v169
	s_add_i32 m0, s19, 0x10000
	v_add_u32_e32 v5, v15, v16
	v_mul_lo_u32 v6, v9, s18
	s_mul_i32 s11, s92, s2
	global_load_lds_dwordx4 v180, s[4:5]
	s_add_i32 m0, s19, 0x12000
	v_add_lshl_u32 v176, v6, v5, 1
	s_add_u32 s26, s14, s11
	v_mul_lo_u32 v17, v7, s20
	global_load_lds_dwordx4 v176, s[4:5]
	s_addc_u32 s27, s15, s9
	s_mov_b32 m0, s19
	s_add_i32 s21, s19, 0x2000
	v_add_lshl_u32 v174, v5, v17, 1
	global_load_lds_dwordx4 v178, s[26:27]
	s_mov_b32 m0, s21
	s_add_u32 s12, s4, s90
	global_load_lds_dwordx4 v174, s[26:27]
	s_addc_u32 s13, s5, s91
	s_add_i32 m0, s19, 0x14000
	v_mov_b32_e32 v181, v169
	v_mov_b32_e32 v177, v169
	global_load_lds_dwordx4 v180, s[12:13]
	s_add_i32 m0, s19, 0x16000
	v_lshl_add_u64 v[10:11], s[12:13], 0, v[180:181]
	v_lshl_add_u64 v[12:13], s[12:13], 0, v[176:177]
	global_load_lds_dwordx4 v176, s[12:13]
	s_add_u32 s12, s26, s22
	s_addc_u32 s13, s27, s23
	s_add_i32 s64, s19, 0x4000
	s_mov_b32 m0, s64
	s_add_i32 s65, s19, 0x6000
	global_load_lds_dwordx4 v178, s[12:13]
	s_mov_b32 m0, s65
	v_mov_b32_e32 v179, v169
	global_load_lds_dwordx4 v174, s[12:13]
	v_mov_b32_e32 v175, v169
	v_mov_b32_e32 v227, 0x358637bd
	v_lshl_add_u64 v[2:3], s[4:5], 0, v[180:181]
	v_lshl_add_u64 v[4:5], s[4:5], 0, v[176:177]
	v_lshl_add_u64 v[6:7], s[26:27], 0, v[178:179]
	v_lshl_add_u64 v[8:9], s[26:27], 0, v[174:175]
	s_cmp_lg_u32 s7, 1
	s_cbranch_scc1 .LBB0_744
	s_setprio 1
	s_barrier

.LBB0_760:
	s_add_i32 s38, s46, 2
	s_add_u32 s8, s26, s4
	s_addc_u32 s9, s27, s5
	s_add_u32 s8, s8, 0x100
	s_addc_u32 s9, s9, 0
	s_add_u32 s30, s44, s4
	s_addc_u32 s31, s45, s5
	s_add_i32 s47, 0, 0x10000
	v_add_u32_e32 v144, s47, v193
	ds_read_b128 v[132:135], v144
	ds_read_b128 v[136:139], v144 offset:1024
	ds_read_b128 v[140:143], v144 offset:2048
	ds_read_b128 v[144:147], v144 offset:3072
	s_cmp_eq_u32 s71, s46
	s_cselect_b32 s9, s13, s9
	s_cselect_b32 s8, s12, s8
	s_cselect_b32 s31, s57, s31
	s_cselect_b32 s30, s56, s30
	v_lshl_add_u64 v[190:191], v[128:129], 0, s[4:5]
	s_add_i32 m0, s19, 0xc000
	ds_read_b128 v[148:151], v202
	ds_read_b128 v[152:155], v202 offset:1024
	ds_read_b128 v[156:159], v202 offset:2048
	ds_read_b128 v[160:163], v202 offset:3072
	ds_read_b128 v[164:167], v202 offset:4096
	ds_read_b128 v[204:207], v202 offset:5120
	ds_read_b128 v[208:211], v202 offset:6144
	ds_read_b128 v[212:215], v202 offset:7168
	global_load_lds_dwordx4 v[190:191], off
	v_lshl_add_u64 v[190:191], v[130:131], 0, s[4:5]
	s_add_i32 m0, s19, 0xe000
	s_nop 0
	global_load_lds_dwordx4 v[190:191], off
	s_waitcnt lgkmcnt(8)
	s_barrier
	s_waitcnt lgkmcnt(0)
	s_waitcnt lgkmcnt(0)
	v_mfma_f32_16x16x32_bf16 v[124:127], v[132:135], v[148:151], v[124:127]
	v_mfma_f32_16x16x32_bf16 v[120:123], v[140:143], v[148:151], v[120:123]
	v_mfma_f32_16x16x32_bf16 v[108:111], v[132:135], v[156:159], v[108:111]
	v_mfma_f32_16x16x32_bf16 v[104:107], v[140:143], v[156:159], v[104:107]
	v_mfma_f32_16x16x32_bf16 v[92:95], v[132:135], v[164:167], v[92:95]
	v_mfma_f32_16x16x32_bf16 v[88:91], v[140:143], v[164:167], v[88:91]
	v_mfma_f32_16x16x32_bf16 v[76:79], v[132:135], v[208:211], v[76:79]
	v_mfma_f32_16x16x32_bf16 v[72:75], v[140:143], v[208:211], v[72:75]
	v_mfma_f32_16x16x32_bf16 v[124:127], v[136:139], v[152:155], v[124:127]
	v_mfma_f32_16x16x32_bf16 v[120:123], v[144:147], v[152:155], v[120:123]
	v_mfma_f32_16x16x32_bf16 v[108:111], v[136:139], v[160:163], v[108:111]
	v_mfma_f32_16x16x32_bf16 v[104:107], v[144:147], v[160:163], v[104:107]
	v_mfma_f32_16x16x32_bf16 v[92:95], v[136:139], v[204:207], v[92:95]
	v_mfma_f32_16x16x32_bf16 v[88:91], v[144:147], v[204:207], v[88:91]
	v_mfma_f32_16x16x32_bf16 v[76:79], v[136:139], v[212:215], v[76:79]
	v_mfma_f32_16x16x32_bf16 v[72:75], v[144:147], v[212:215], v[72:75]
	s_barrier
	s_add_i32 s46, 0, 0x14000
	v_add_u32_e32 v190, s46, v193
	s_add_i32 s47, s47, s53
	ds_read_b128 v[216:219], v190
	ds_read_b128 v[220:223], v190 offset:1024
	ds_read_b128 v[232:235], v190 offset:2048
	ds_read_b128 v[240:243], v190 offset:3072
	v_lshl_add_u64 v[190:191], s[30:31], 0, v[180:181]
	s_mov_b32 m0, s47
	v_lshl_add_u64 v[224:225], s[30:31], 0, v[176:177]
	global_load_lds_dwordx4 v[190:191], off
	s_add_i32 m0, s47, 0x2000
	s_nop 0
	global_load_lds_dwordx4 v[224:225], off
	s_barrier
	s_waitcnt lgkmcnt(0)
	s_waitcnt lgkmcnt(0)
	v_mfma_f32_16x16x32_bf16 v[116:119], v[216:219], v[148:151], v[116:119]
	v_mfma_f32_16x16x32_bf16 v[112:115], v[232:235], v[148:151], v[112:115]
	v_mfma_f32_16x16x32_bf16 v[100:103], v[216:219], v[156:159], v[100:103]
	v_mfma_f32_16x16x32_bf16 v[96:99], v[232:235], v[156:159], v[96:99]
	v_mfma_f32_16x16x32_bf16 v[84:87], v[216:219], v[164:167], v[84:87]
	v_mfma_f32_16x16x32_bf16 v[80:83], v[232:235], v[164:167], v[80:83]
	v_mfma_f32_16x16x32_bf16 v[68:71], v[216:219], v[208:211], v[68:71]
	v_mfma_f32_16x16x32_bf16 v[64:67], v[232:235], v[208:211], v[64:67]
	v_mfma_f32_16x16x32_bf16 v[116:119], v[220:223], v[152:155], v[116:119]
	v_mfma_f32_16x16x32_bf16 v[112:115], v[240:243], v[152:155], v[112:115]
	v_mfma_f32_16x16x32_bf16 v[100:103], v[220:223], v[160:163], v[100:103]
	v_mfma_f32_16x16x32_bf16 v[96:99], v[240:243], v[160:163], v[96:99]
	v_mfma_f32_16x16x32_bf16 v[84:87], v[220:223], v[204:207], v[84:87]
	v_mfma_f32_16x16x32_bf16 v[80:83], v[240:243], v[204:207], v[80:83]
	v_mfma_f32_16x16x32_bf16 v[68:71], v[220:223], v[212:215], v[68:71]
	v_mfma_f32_16x16x32_bf16 v[64:67], v[240:243], v[212:215], v[64:67]
	s_mov_b32 m0, s19
	v_lshl_add_u64 v[244:245], s[8:9], 0, v[178:179]
	s_barrier
	ds_read_b128 v[148:151], v202 offset:16384
	ds_read_b128 v[152:155], v202 offset:17408
	ds_read_b128 v[156:159], v202 offset:18432
	ds_read_b128 v[160:163], v202 offset:19456
	ds_read_b128 v[164:167], v202 offset:20480
	ds_read_b128 v[204:207], v202 offset:21504
	ds_read_b128 v[208:211], v202 offset:22528
	ds_read_b128 v[212:215], v202 offset:23552
	global_load_lds_dwordx4 v[244:245], off
	v_lshl_add_u64 v[246:247], s[8:9], 0, v[174:175]
	s_mov_b32 m0, s21
	s_nop 0
	global_load_lds_dwordx4 v[246:247], off
	s_barrier
	s_waitcnt lgkmcnt(0)
	s_waitcnt lgkmcnt(0)
	v_mfma_f32_16x16x32_bf16 v[60:63], v[132:135], v[148:151], v[60:63]
	v_mfma_f32_16x16x32_bf16 v[56:59], v[140:143], v[148:151], v[56:59]
	v_mfma_f32_16x16x32_bf16 v[44:47], v[132:135], v[156:159], v[44:47]
	v_mfma_f32_16x16x32_bf16 v[40:43], v[140:143], v[156:159], v[40:43]
	v_mfma_f32_16x16x32_bf16 v[28:31], v[132:135], v[164:167], v[28:31]
	v_mfma_f32_16x16x32_bf16 v[24:27], v[140:143], v[164:167], v[24:27]
	v_mfma_f32_16x16x32_bf16 v[12:15], v[132:135], v[208:211], v[12:15]
	v_mfma_f32_16x16x32_bf16 v[8:11], v[140:143], v[208:211], v[8:11]
	v_mfma_f32_16x16x32_bf16 v[60:63], v[136:139], v[152:155], v[60:63]
	v_mfma_f32_16x16x32_bf16 v[56:59], v[144:147], v[152:155], v[56:59]
	v_mfma_f32_16x16x32_bf16 v[44:47], v[136:139], v[160:163], v[44:47]
	v_mfma_f32_16x16x32_bf16 v[40:43], v[144:147], v[160:163], v[40:43]
	v_mfma_f32_16x16x32_bf16 v[28:31], v[136:139], v[204:207], v[28:31]
	v_mfma_f32_16x16x32_bf16 v[24:27], v[144:147], v[204:207], v[24:27]
	v_mfma_f32_16x16x32_bf16 v[12:15], v[136:139], v[212:215], v[12:15]
	v_mfma_f32_16x16x32_bf16 v[8:11], v[144:147], v[212:215], v[8:11]
	s_barrier
	s_add_u32 s30, s30, s90
	s_addc_u32 s31, s31, s91
	s_add_i32 s46, s46, s53
	v_lshl_add_u64 v[248:249], s[30:31], 0, v[180:181]
	s_mov_b32 m0, s46
	v_lshl_add_u64 v[250:251], s[30:31], 0, v[176:177]
	global_load_lds_dwordx4 v[248:249], off
	s_add_i32 m0, s46, 0x2000
	s_nop 0
	global_load_lds_dwordx4 v[250:251], off
	s_waitcnt vmcnt(6)
	s_barrier
	v_mfma_f32_16x16x32_bf16 v[52:55], v[216:219], v[148:151], v[52:55]
	v_mfma_f32_16x16x32_bf16 v[48:51], v[232:235], v[148:151], v[48:51]
	v_mfma_f32_16x16x32_bf16 v[36:39], v[216:219], v[156:159], v[36:39]
	v_mfma_f32_16x16x32_bf16 v[32:35], v[232:235], v[156:159], v[32:35]
	v_mfma_f32_16x16x32_bf16 v[20:23], v[216:219], v[164:167], v[20:23]
	v_mfma_f32_16x16x32_bf16 v[16:19], v[232:235], v[164:167], v[16:19]
	v_mfma_f32_16x16x32_bf16 v[4:7], v[216:219], v[208:211], v[4:7]
	v_mfma_f32_16x16x32_bf16 v[0:3], v[232:235], v[208:211], v[0:3]
	v_mfma_f32_16x16x32_bf16 v[52:55], v[220:223], v[152:155], v[52:55]
	v_mfma_f32_16x16x32_bf16 v[48:51], v[240:243], v[152:155], v[48:51]
	v_mfma_f32_16x16x32_bf16 v[36:39], v[220:223], v[160:163], v[36:39]
	v_mfma_f32_16x16x32_bf16 v[32:35], v[240:243], v[160:163], v[32:35]
	v_mfma_f32_16x16x32_bf16 v[20:23], v[220:223], v[204:207], v[20:23]
	v_mfma_f32_16x16x32_bf16 v[16:19], v[240:243], v[204:207], v[16:19]
	v_mfma_f32_16x16x32_bf16 v[4:7], v[220:223], v[212:215], v[4:7]
	v_mfma_f32_16x16x32_bf16 v[0:3], v[240:243], v[212:215], v[0:3]
	v_add_u32_e32 v144, s77, v193
	s_barrier
	ds_read_b128 v[132:135], v144
	ds_read_b128 v[136:139], v144 offset:1024
	ds_read_b128 v[140:143], v144 offset:2048
	ds_read_b128 v[144:147], v144 offset:3072
	s_add_u32 s8, s8, s22
	s_addc_u32 s9, s9, s23
	s_mov_b32 m0, s64
	v_lshl_add_u64 v[216:217], s[8:9], 0, v[178:179]
	ds_read_b128 v[148:151], v202 offset:32768
	ds_read_b128 v[152:155], v202 offset:33792
	ds_read_b128 v[156:159], v202 offset:34816
	ds_read_b128 v[160:163], v202 offset:35840
	ds_read_b128 v[164:167], v202 offset:36864
	ds_read_b128 v[204:207], v202 offset:37888
	ds_read_b128 v[208:211], v202 offset:38912
	ds_read_b128 v[212:215], v202 offset:39936
	global_load_lds_dwordx4 v[216:217], off
	v_lshl_add_u64 v[216:217], s[8:9], 0, v[174:175]
	s_mov_b32 m0, s65
	s_nop 0
	global_load_lds_dwordx4 v[216:217], off
	s_waitcnt lgkmcnt(8)
	s_barrier
	s_waitcnt lgkmcnt(0)
	s_waitcnt lgkmcnt(0)
	v_mfma_f32_16x16x32_bf16 v[124:127], v[132:135], v[148:151], v[124:127]
	v_mfma_f32_16x16x32_bf16 v[120:123], v[140:143], v[148:151], v[120:123]
	v_mfma_f32_16x16x32_bf16 v[108:111], v[132:135], v[156:159], v[108:111]
	v_mfma_f32_16x16x32_bf16 v[104:107], v[140:143], v[156:159], v[104:107]
	v_mfma_f32_16x16x32_bf16 v[92:95], v[132:135], v[164:167], v[92:95]
	v_mfma_f32_16x16x32_bf16 v[88:91], v[140:143], v[164:167], v[88:91]
	v_mfma_f32_16x16x32_bf16 v[76:79], v[132:135], v[208:211], v[76:79]
	v_mfma_f32_16x16x32_bf16 v[72:75], v[140:143], v[208:211], v[72:75]
	v_mfma_f32_16x16x32_bf16 v[124:127], v[136:139], v[152:155], v[124:127]
	v_mfma_f32_16x16x32_bf16 v[120:123], v[144:147], v[152:155], v[120:123]
	v_mfma_f32_16x16x32_bf16 v[108:111], v[136:139], v[160:163], v[108:111]
	v_mfma_f32_16x16x32_bf16 v[104:107], v[144:147], v[160:163], v[104:107]
	v_mfma_f32_16x16x32_bf16 v[92:95], v[136:139], v[204:207], v[92:95]
	v_mfma_f32_16x16x32_bf16 v[88:91], v[144:147], v[204:207], v[88:91]
	v_mfma_f32_16x16x32_bf16 v[76:79], v[136:139], v[212:215], v[76:79]
	v_mfma_f32_16x16x32_bf16 v[72:75], v[144:147], v[212:215], v[72:75]
	s_barrier
	s_add_i32 s8, 0, 0x1c000
	s_add_i32 s9, s77, s53
	v_add_u32_e32 v203, s8, v193
	v_lshl_add_u64 v[190:191], v[190:191], 0, s[58:59]
	s_mov_b32 m0, s9
	ds_read_b128 v[216:219], v203
	ds_read_b128 v[220:223], v203 offset:1024
	ds_read_b128 v[232:235], v203 offset:2048
	ds_read_b128 v[240:243], v203 offset:3072
	global_load_lds_dwordx4 v[190:191], off
	v_lshl_add_u64 v[190:191], v[224:225], 0, s[58:59]
	s_add_i32 m0, s9, 0x2000
	s_nop 0
	global_load_lds_dwordx4 v[190:191], off
	s_barrier
	s_waitcnt lgkmcnt(0)
	s_waitcnt lgkmcnt(0)
	v_mfma_f32_16x16x32_bf16 v[116:119], v[216:219], v[148:151], v[116:119]
	v_mfma_f32_16x16x32_bf16 v[112:115], v[232:235], v[148:151], v[112:115]
	v_mfma_f32_16x16x32_bf16 v[100:103], v[216:219], v[156:159], v[100:103]
	v_mfma_f32_16x16x32_bf16 v[96:99], v[232:235], v[156:159], v[96:99]
	v_mfma_f32_16x16x32_bf16 v[84:87], v[216:219], v[164:167], v[84:87]
	v_mfma_f32_16x16x32_bf16 v[80:83], v[232:235], v[164:167], v[80:83]
	v_mfma_f32_16x16x32_bf16 v[68:71], v[216:219], v[208:211], v[68:71]
	v_mfma_f32_16x16x32_bf16 v[64:67], v[232:235], v[208:211], v[64:67]
	v_mfma_f32_16x16x32_bf16 v[116:119], v[220:223], v[152:155], v[116:119]
	v_mfma_f32_16x16x32_bf16 v[112:115], v[240:243], v[152:155], v[112:115]
	v_mfma_f32_16x16x32_bf16 v[100:103], v[220:223], v[160:163], v[100:103]
	v_mfma_f32_16x16x32_bf16 v[96:99], v[240:243], v[160:163], v[96:99]
	v_mfma_f32_16x16x32_bf16 v[84:87], v[220:223], v[204:207], v[84:87]
	v_mfma_f32_16x16x32_bf16 v[80:83], v[240:243], v[204:207], v[80:83]
	v_mfma_f32_16x16x32_bf16 v[68:71], v[220:223], v[212:215], v[68:71]
	v_mfma_f32_16x16x32_bf16 v[64:67], v[240:243], v[212:215], v[64:67]
	s_mov_b32 m0, s66
	v_lshl_add_u64 v[190:191], v[244:245], 0, s[58:59]
	s_barrier
	ds_read_b128 v[148:151], v202 offset:49152
	ds_read_b128 v[152:155], v202 offset:50176
	ds_read_b128 v[156:159], v202 offset:51200
	ds_read_b128 v[160:163], v202 offset:52224
	ds_read_b128 v[164:167], v202 offset:53248
	ds_read_b128 v[204:207], v202 offset:54272
	ds_read_b128 v[208:211], v202 offset:55296
	ds_read_b128 v[212:215], v202 offset:56320
	global_load_lds_dwordx4 v[190:191], off
	v_lshl_add_u64 v[190:191], v[246:247], 0, s[58:59]
	s_mov_b32 m0, s67
	s_nop 0
	global_load_lds_dwordx4 v[190:191], off
	s_barrier
	s_waitcnt lgkmcnt(0)
	s_waitcnt lgkmcnt(0)
	v_mfma_f32_16x16x32_bf16 v[60:63], v[132:135], v[148:151], v[60:63]
	v_mfma_f32_16x16x32_bf16 v[56:59], v[140:143], v[148:151], v[56:59]
	v_mfma_f32_16x16x32_bf16 v[44:47], v[132:135], v[156:159], v[44:47]
	v_mfma_f32_16x16x32_bf16 v[40:43], v[140:143], v[156:159], v[40:43]
	v_mfma_f32_16x16x32_bf16 v[28:31], v[132:135], v[164:167], v[28:31]
	v_mfma_f32_16x16x32_bf16 v[24:27], v[140:143], v[164:167], v[24:27]
	v_mfma_f32_16x16x32_bf16 v[12:15], v[132:135], v[208:211], v[12:15]
	v_mfma_f32_16x16x32_bf16 v[8:11], v[140:143], v[208:211], v[8:11]
	v_mfma_f32_16x16x32_bf16 v[60:63], v[136:139], v[152:155], v[60:63]
	v_mfma_f32_16x16x32_bf16 v[56:59], v[144:147], v[152:155], v[56:59]
	v_mfma_f32_16x16x32_bf16 v[44:47], v[136:139], v[160:163], v[44:47]
	v_mfma_f32_16x16x32_bf16 v[40:43], v[144:147], v[160:163], v[40:43]
	v_mfma_f32_16x16x32_bf16 v[28:31], v[136:139], v[204:207], v[28:31]
	v_mfma_f32_16x16x32_bf16 v[24:27], v[144:147], v[204:207], v[24:27]
	v_mfma_f32_16x16x32_bf16 v[12:15], v[136:139], v[212:215], v[12:15]
	v_mfma_f32_16x16x32_bf16 v[8:11], v[144:147], v[212:215], v[8:11]
	s_barrier
	s_add_i32 s8, s8, s53
	v_lshl_add_u64 v[132:133], v[248:249], 0, s[58:59]
	s_mov_b32 m0, s8
	s_nop 0
	global_load_lds_dwordx4 v[132:133], off
	v_lshl_add_u64 v[132:133], v[250:251], 0, s[58:59]
	s_add_i32 m0, s8, 0x2000
	s_nop 0
	global_load_lds_dwordx4 v[132:133], off
	s_waitcnt vmcnt(6)
	s_barrier
	v_mfma_f32_16x16x32_bf16 v[52:55], v[216:219], v[148:151], v[52:55]
	v_mfma_f32_16x16x32_bf16 v[48:51], v[232:235], v[148:151], v[48:51]
	v_mfma_f32_16x16x32_bf16 v[36:39], v[216:219], v[156:159], v[36:39]
	v_mfma_f32_16x16x32_bf16 v[32:35], v[232:235], v[156:159], v[32:35]
	v_mfma_f32_16x16x32_bf16 v[20:23], v[216:219], v[164:167], v[20:23]
	v_mfma_f32_16x16x32_bf16 v[16:19], v[232:235], v[164:167], v[16:19]
	v_mfma_f32_16x16x32_bf16 v[4:7], v[216:219], v[208:211], v[4:7]
	v_mfma_f32_16x16x32_bf16 v[0:3], v[232:235], v[208:211], v[0:3]
	v_mfma_f32_16x16x32_bf16 v[52:55], v[220:223], v[152:155], v[52:55]
	v_mfma_f32_16x16x32_bf16 v[48:51], v[240:243], v[152:155], v[48:51]
	v_mfma_f32_16x16x32_bf16 v[36:39], v[220:223], v[160:163], v[36:39]
	v_mfma_f32_16x16x32_bf16 v[32:35], v[240:243], v[160:163], v[32:35]
	v_mfma_f32_16x16x32_bf16 v[20:23], v[220:223], v[204:207], v[20:23]
	v_mfma_f32_16x16x32_bf16 v[16:19], v[240:243], v[204:207], v[16:19]
	v_mfma_f32_16x16x32_bf16 v[4:7], v[220:223], v[212:215], v[4:7]
	v_mfma_f32_16x16x32_bf16 v[0:3], v[240:243], v[212:215], v[0:3]
	s_add_u32 s4, s4, 0x100
	s_addc_u32 s5, s5, 0
	s_cmp_ge_i32 s38, s68
	s_barrier
	s_cbranch_scc0 .LBB0_753
	s_load_dwordx2 s[26:27], s[0:1], 0x150
	s_mov_b64 s[4:5], -1
	s_mov_b64 s[8:9], 0
	s_cmp_lt_i32 s50, 5
	s_mov_b64 s[44:45], 0
	s_cbranch_scc1 .LBB0_785
	s_cmp_gt_i32 s50, 7
	s_cbranch_scc0 .LBB0_775
	s_cmp_gt_i32 s50, 8
	s_cbranch_scc0 .LBB0_772
	s_cmp_gt_i32 s50, 10
	s_cbranch_scc0 .LBB0_768
	s_cmp_eq_u32 s50, 11
	s_mov_b64 s[44:45], -1
	s_cbranch_scc0 .LBB0_767
	s_waitcnt lgkmcnt(0)
	s_add_u32 s4, s26, 0x9640000
	s_addc_u32 s5, s27, 0
	s_lshl_b32 s38, s70, 1
	s_add_u32 s30, s26, s38
	s_addc_u32 s31, s27, 0
	v_lshlrev_b32_e32 v128, 1, v172
	v_mov_b32_e32 v129, v169
	v_lshl_add_u64 v[130:131], s[30:31], 0, v[128:129]
	s_lshl_b64 s[30:31], s[24:25], 1
	v_add_u32_e32 v132, s54, v192
	v_lshl_add_u64 v[130:131], v[130:131], 0, s[30:31]
	s_mov_b64 s[44:45], 0x1a642000
	v_lshl_add_u64 v[130:131], v[130:131], 0, s[44:45]
	v_or_b32_e32 v133, 16, v132
	v_mad_i64_i32 v[142:143], s[44:45], v133, s37, v[130:131]
	v_or_b32_e32 v133, 32, v132
	v_mad_i64_i32 v[150:151], s[44:45], v133, s37, v[130:131]
	v_or_b32_e32 v133, 48, v132
	v_mad_i64_i32 v[134:135], s[44:45], v132, s37, v[130:131]
	v_mad_i64_i32 v[158:159], s[44:45], v133, s37, v[130:131]
	global_load_dwordx2 v[136:137], v[134:135], off
	global_load_dwordx2 v[138:139], v[134:135], off offset:32
	global_load_dwordx2 v[140:141], v[134:135], off offset:256
	s_nop 0
	global_load_dwordx2 v[134:135], v[134:135], off offset:288
	s_nop 0
	global_load_dwordx2 v[144:145], v[142:143], off
	global_load_dwordx2 v[146:147], v[142:143], off offset:32
	global_load_dwordx2 v[148:149], v[142:143], off offset:256
	s_nop 0
	global_load_dwordx2 v[142:143], v[142:143], off offset:288
	s_nop 0
	global_load_dwordx2 v[152:153], v[150:151], off
	global_load_dwordx2 v[154:155], v[150:151], off offset:32
	global_load_dwordx2 v[156:157], v[150:151], off offset:256
	s_nop 0
	global_load_dwordx2 v[150:151], v[150:151], off offset:288
	s_nop 0
	global_load_dwordx2 v[160:161], v[158:159], off
	global_load_dwordx2 v[162:163], v[158:159], off offset:32
	global_load_dwordx2 v[164:165], v[158:159], off offset:256
	s_nop 0
	global_load_dwordx2 v[158:159], v[158:159], off offset:288
	v_ashrrev_i32_e32 v133, 31, v132
	s_waitcnt vmcnt(0)
	v_lshlrev_b32_e32 v166, 16, v136
	v_and_b32_e32 v136, 0xffff0000, v136
	v_lshlrev_b64 v[132:133], 12, v[132:133]
	v_mul_f32_e32 v166, v124, v166
	v_mul_f32_e32 v136, v125, v136
	v_lshl_add_u64 v[132:133], s[4:5], 0, v[132:133]
	v_cvt_pk_bf16_f32 v136, v166, v136
	v_lshlrev_b32_e32 v166, 16, v137
	v_and_b32_e32 v137, 0xffff0000, v137
	v_lshl_add_u64 v[132:133], v[132:133], 0, s[30:31]
	v_mul_f32_e32 v137, v127, v137
	v_lshl_add_u64 v[132:133], v[132:133], 0, s[38:39]
	v_mul_f32_e32 v166, v126, v166
	v_cvt_pk_bf16_f32 v137, v166, v137
	v_lshl_add_u64 v[132:133], v[132:133], 0, v[128:129]
	global_store_dwordx2 v[132:133], v[136:137], off
	v_lshlrev_b32_e32 v136, 16, v138
	v_and_b32_e32 v137, 0xffff0000, v138
	v_mul_f32_e32 v136, v120, v136
	v_mul_f32_e32 v137, v121, v137
	v_cvt_pk_bf16_f32 v136, v136, v137
	v_lshlrev_b32_e32 v137, 16, v139
	v_mul_f32_e32 v137, v122, v137
	v_and_b32_e32 v138, 0xffff0000, v139
	v_mul_f32_e32 v138, v123, v138
	v_cvt_pk_bf16_f32 v137, v137, v138
	global_store_dwordx2 v[132:133], v[136:137], off offset:32
	v_lshlrev_b32_e32 v136, 16, v140
	v_and_b32_e32 v137, 0xffff0000, v140
	v_mul_f32_e32 v136, v116, v136
	v_mul_f32_e32 v137, v117, v137
	v_cvt_pk_bf16_f32 v136, v136, v137
	v_lshlrev_b32_e32 v137, 16, v141
	v_mul_f32_e32 v137, v118, v137
	v_and_b32_e32 v138, 0xffff0000, v141
	v_mul_f32_e32 v138, v119, v138
	v_cvt_pk_bf16_f32 v137, v137, v138
	global_store_dwordx2 v[132:133], v[136:137], off offset:256
	v_lshlrev_b32_e32 v136, 16, v134
	v_and_b32_e32 v134, 0xffff0000, v134
	v_mul_f32_e32 v136, v112, v136
	v_mul_f32_e32 v134, v113, v134
	v_cvt_pk_bf16_f32 v134, v136, v134
	v_lshlrev_b32_e32 v136, 16, v135
	v_and_b32_e32 v135, 0xffff0000, v135
	v_mul_f32_e32 v135, v115, v135
	v_mul_f32_e32 v136, v114, v136
	v_cvt_pk_bf16_f32 v135, v136, v135
	global_store_dwordx2 v[132:133], v[134:135], off offset:288
	v_lshlrev_b32_e32 v132, 16, v144
	v_and_b32_e32 v133, 0xffff0000, v144
	v_mul_f32_e32 v132, v108, v132
	v_mul_f32_e32 v133, v109, v133
	v_cvt_pk_bf16_f32 v132, v132, v133
	v_lshlrev_b32_e32 v133, 16, v145
	v_and_b32_e32 v134, 0xffff0000, v145
	v_mul_f32_e32 v133, v110, v133
	v_mul_f32_e32 v134, v111, v134
	v_cvt_pk_bf16_f32 v133, v133, v134
	v_add_u32_e32 v134, s54, v194
	v_ashrrev_i32_e32 v135, 31, v134
	v_lshlrev_b64 v[134:135], 12, v[134:135]
	v_lshl_add_u64 v[134:135], s[4:5], 0, v[134:135]
	v_lshl_add_u64 v[134:135], v[134:135], 0, s[30:31]
	v_lshl_add_u64 v[134:135], v[134:135], 0, s[38:39]
	v_lshl_add_u64 v[134:135], v[134:135], 0, v[128:129]
	global_store_dwordx2 v[134:135], v[132:133], off
	v_lshlrev_b32_e32 v132, 16, v146
	v_and_b32_e32 v133, 0xffff0000, v146
	v_mul_f32_e32 v132, v104, v132
	v_mul_f32_e32 v133, v105, v133
	v_cvt_pk_bf16_f32 v132, v132, v133
	v_lshlrev_b32_e32 v133, 16, v147
	v_mul_f32_e32 v133, v106, v133
	v_and_b32_e32 v136, 0xffff0000, v147
	v_mul_f32_e32 v136, v107, v136
	v_cvt_pk_bf16_f32 v133, v133, v136
	global_store_dwordx2 v[134:135], v[132:133], off offset:32
	v_lshlrev_b32_e32 v132, 16, v148
	v_and_b32_e32 v133, 0xffff0000, v148
	v_mul_f32_e32 v132, v100, v132
	v_mul_f32_e32 v133, v101, v133
	v_cvt_pk_bf16_f32 v132, v132, v133
	v_lshlrev_b32_e32 v133, 16, v149
	v_mul_f32_e32 v133, v102, v133
	v_and_b32_e32 v136, 0xffff0000, v149
	v_mul_f32_e32 v136, v103, v136
	v_cvt_pk_bf16_f32 v133, v133, v136
	global_store_dwordx2 v[134:135], v[132:133], off offset:256
	v_lshlrev_b32_e32 v132, 16, v142
	v_and_b32_e32 v133, 0xffff0000, v142
	v_mul_f32_e32 v132, v96, v132
	v_mul_f32_e32 v133, v97, v133
	v_cvt_pk_bf16_f32 v132, v132, v133
	v_lshlrev_b32_e32 v133, 16, v143
	v_mul_f32_e32 v133, v98, v133
	v_and_b32_e32 v136, 0xffff0000, v143
	v_mul_f32_e32 v136, v99, v136
	v_cvt_pk_bf16_f32 v133, v133, v136
	global_store_dwordx2 v[134:135], v[132:133], off offset:288
	v_lshlrev_b32_e32 v132, 16, v152
	v_and_b32_e32 v133, 0xffff0000, v152
	v_mul_f32_e32 v132, v92, v132
	v_mul_f32_e32 v133, v93, v133
	v_cvt_pk_bf16_f32 v132, v132, v133
	v_lshlrev_b32_e32 v133, 16, v153
	v_and_b32_e32 v134, 0xffff0000, v153
	v_mul_f32_e32 v133, v94, v133
	v_mul_f32_e32 v134, v95, v134
	v_cvt_pk_bf16_f32 v133, v133, v134
	v_add_u32_e32 v134, s54, v195
	v_ashrrev_i32_e32 v135, 31, v134
	v_lshlrev_b64 v[134:135], 12, v[134:135]
	v_lshl_add_u64 v[134:135], s[4:5], 0, v[134:135]
	v_lshl_add_u64 v[134:135], v[134:135], 0, s[30:31]
	v_lshl_add_u64 v[134:135], v[134:135], 0, s[38:39]
	v_lshl_add_u64 v[134:135], v[134:135], 0, v[128:129]
	global_store_dwordx2 v[134:135], v[132:133], off
	v_lshlrev_b32_e32 v132, 16, v154
	v_and_b32_e32 v133, 0xffff0000, v154
	v_mul_f32_e32 v132, v88, v132
	v_mul_f32_e32 v133, v89, v133
	v_cvt_pk_bf16_f32 v132, v132, v133
	v_lshlrev_b32_e32 v133, 16, v155
	v_mul_f32_e32 v133, v90, v133
	v_and_b32_e32 v136, 0xffff0000, v155
	v_mul_f32_e32 v136, v91, v136
	v_cvt_pk_bf16_f32 v133, v133, v136
	global_store_dwordx2 v[134:135], v[132:133], off offset:32
	v_lshlrev_b32_e32 v132, 16, v156
	v_and_b32_e32 v133, 0xffff0000, v156
	v_mul_f32_e32 v132, v84, v132
	v_mul_f32_e32 v133, v85, v133
	v_cvt_pk_bf16_f32 v132, v132, v133
	v_lshlrev_b32_e32 v133, 16, v157
	v_mul_f32_e32 v133, v86, v133
	v_and_b32_e32 v136, 0xffff0000, v157
	v_mul_f32_e32 v136, v87, v136
	v_cvt_pk_bf16_f32 v133, v133, v136
	global_store_dwordx2 v[134:135], v[132:133], off offset:256
	v_lshlrev_b32_e32 v132, 16, v150
	v_and_b32_e32 v133, 0xffff0000, v150
	v_mul_f32_e32 v132, v80, v132
	v_mul_f32_e32 v133, v81, v133
	v_cvt_pk_bf16_f32 v132, v132, v133
	v_lshlrev_b32_e32 v133, 16, v151
	v_mul_f32_e32 v133, v82, v133
	v_and_b32_e32 v136, 0xffff0000, v151
	v_mul_f32_e32 v136, v83, v136
	v_cvt_pk_bf16_f32 v133, v133, v136
	global_store_dwordx2 v[134:135], v[132:133], off offset:288
	v_lshlrev_b32_e32 v132, 16, v160
	v_and_b32_e32 v133, 0xffff0000, v160
	v_mul_f32_e32 v132, v76, v132
	v_mul_f32_e32 v133, v77, v133
	v_cvt_pk_bf16_f32 v132, v132, v133
	v_lshlrev_b32_e32 v133, 16, v161
	v_and_b32_e32 v134, 0xffff0000, v161
	v_mul_f32_e32 v133, v78, v133
	v_mul_f32_e32 v134, v79, v134
	v_cvt_pk_bf16_f32 v133, v133, v134
	v_add_u32_e32 v134, s54, v196
	v_ashrrev_i32_e32 v135, 31, v134
	v_lshlrev_b64 v[134:135], 12, v[134:135]
	v_lshl_add_u64 v[134:135], s[4:5], 0, v[134:135]
	v_lshl_add_u64 v[134:135], v[134:135], 0, s[30:31]
	v_lshl_add_u64 v[134:135], v[134:135], 0, s[38:39]
	v_lshl_add_u64 v[134:135], v[134:135], 0, v[128:129]
	global_store_dwordx2 v[134:135], v[132:133], off
	v_lshlrev_b32_e32 v132, 16, v162
	v_and_b32_e32 v133, 0xffff0000, v162
	v_mul_f32_e32 v132, v72, v132
	v_mul_f32_e32 v133, v73, v133
	v_cvt_pk_bf16_f32 v132, v132, v133
	v_lshlrev_b32_e32 v133, 16, v163
	v_mul_f32_e32 v133, v74, v133
	v_and_b32_e32 v136, 0xffff0000, v163
	v_mul_f32_e32 v136, v75, v136
	v_cvt_pk_bf16_f32 v133, v133, v136
	global_store_dwordx2 v[134:135], v[132:133], off offset:32
	v_lshlrev_b32_e32 v132, 16, v164
	v_and_b32_e32 v133, 0xffff0000, v164
	v_mul_f32_e32 v132, v68, v132
	v_mul_f32_e32 v133, v69, v133
	v_cvt_pk_bf16_f32 v132, v132, v133
	v_lshlrev_b32_e32 v133, 16, v165
	v_mul_f32_e32 v133, v70, v133
	v_and_b32_e32 v136, 0xffff0000, v165
	v_mul_f32_e32 v136, v71, v136
	v_cvt_pk_bf16_f32 v133, v133, v136
	global_store_dwordx2 v[134:135], v[132:133], off offset:256
	v_lshlrev_b32_e32 v132, 16, v158
	v_and_b32_e32 v133, 0xffff0000, v158
	v_mul_f32_e32 v132, v64, v132
	v_mul_f32_e32 v133, v65, v133
	v_cvt_pk_bf16_f32 v132, v132, v133
	v_lshlrev_b32_e32 v133, 16, v159
	v_mul_f32_e32 v133, v66, v133
	v_and_b32_e32 v136, 0xffff0000, v159
	v_mul_f32_e32 v136, v67, v136
	v_cvt_pk_bf16_f32 v133, v133, v136
	global_store_dwordx2 v[134:135], v[132:133], off offset:288
	v_add_u32_e32 v132, s54, v197
	v_or_b32_e32 v133, 16, v132
	v_mad_i64_i32 v[142:143], s[44:45], v133, s37, v[130:131]
	v_or_b32_e32 v133, 32, v132
	v_mad_i64_i32 v[150:151], s[44:45], v133, s37, v[130:131]
	v_or_b32_e32 v133, 48, v132
	v_mad_i64_i32 v[134:135], s[44:45], v132, s37, v[130:131]
	v_mad_i64_i32 v[130:131], s[44:45], v133, s37, v[130:131]
	global_load_dwordx2 v[136:137], v[134:135], off
	global_load_dwordx2 v[138:139], v[134:135], off offset:32
	global_load_dwordx2 v[140:141], v[134:135], off offset:256
	s_nop 0
	global_load_dwordx2 v[134:135], v[134:135], off offset:288
	s_nop 0
	global_load_dwordx2 v[144:145], v[142:143], off
	global_load_dwordx2 v[146:147], v[142:143], off offset:32
	global_load_dwordx2 v[148:149], v[142:143], off offset:256
	s_nop 0
	global_load_dwordx2 v[142:143], v[142:143], off offset:288
	s_nop 0
	global_load_dwordx2 v[152:153], v[150:151], off
	global_load_dwordx2 v[154:155], v[150:151], off offset:32
	global_load_dwordx2 v[156:157], v[150:151], off offset:256
	s_nop 0
	global_load_dwordx2 v[150:151], v[150:151], off offset:288
	s_nop 0
	global_load_dwordx2 v[158:159], v[130:131], off
	global_load_dwordx2 v[160:161], v[130:131], off offset:32
	global_load_dwordx2 v[162:163], v[130:131], off offset:256
	s_nop 0
	global_load_dwordx2 v[130:131], v[130:131], off offset:288
	v_ashrrev_i32_e32 v133, 31, v132
	s_waitcnt vmcnt(15)
	v_lshlrev_b32_e32 v164, 16, v136
	v_and_b32_e32 v136, 0xffff0000, v136
	v_lshlrev_b64 v[132:133], 12, v[132:133]
	v_mul_f32_e32 v164, v60, v164
	v_mul_f32_e32 v136, v61, v136
	v_lshl_add_u64 v[132:133], s[4:5], 0, v[132:133]
	v_cvt_pk_bf16_f32 v136, v164, v136
	v_lshlrev_b32_e32 v164, 16, v137
	v_and_b32_e32 v137, 0xffff0000, v137
	v_lshl_add_u64 v[132:133], v[132:133], 0, s[30:31]
	v_mul_f32_e32 v137, v63, v137
	v_lshl_add_u64 v[132:133], v[132:133], 0, s[38:39]
	v_mul_f32_e32 v164, v62, v164
	v_cvt_pk_bf16_f32 v137, v164, v137
	v_lshl_add_u64 v[132:133], v[132:133], 0, v[128:129]
	global_store_dwordx2 v[132:133], v[136:137], off
	s_waitcnt vmcnt(15)
	v_lshlrev_b32_e32 v136, 16, v138
	v_and_b32_e32 v137, 0xffff0000, v138
	v_mul_f32_e32 v136, v56, v136
	v_mul_f32_e32 v137, v57, v137
	v_cvt_pk_bf16_f32 v136, v136, v137
	v_lshlrev_b32_e32 v137, 16, v139
	v_mul_f32_e32 v137, v58, v137
	v_and_b32_e32 v138, 0xffff0000, v139
	v_mul_f32_e32 v138, v59, v138
	v_cvt_pk_bf16_f32 v137, v137, v138
	global_store_dwordx2 v[132:133], v[136:137], off offset:32
	s_waitcnt vmcnt(15)
	v_lshlrev_b32_e32 v136, 16, v140
	v_and_b32_e32 v137, 0xffff0000, v140
	v_mul_f32_e32 v136, v52, v136
	v_mul_f32_e32 v137, v53, v137
	v_cvt_pk_bf16_f32 v136, v136, v137
	v_lshlrev_b32_e32 v137, 16, v141
	v_mul_f32_e32 v137, v54, v137
	v_and_b32_e32 v138, 0xffff0000, v141
	v_mul_f32_e32 v138, v55, v138
	v_cvt_pk_bf16_f32 v137, v137, v138
	global_store_dwordx2 v[132:133], v[136:137], off offset:256
	s_waitcnt vmcnt(15)
	v_lshlrev_b32_e32 v136, 16, v134
	v_and_b32_e32 v134, 0xffff0000, v134
	v_mul_f32_e32 v136, v48, v136
	v_mul_f32_e32 v134, v49, v134
	v_cvt_pk_bf16_f32 v134, v136, v134
	v_lshlrev_b32_e32 v136, 16, v135
	v_and_b32_e32 v135, 0xffff0000, v135
	v_mul_f32_e32 v135, v51, v135
	v_mul_f32_e32 v136, v50, v136
	v_cvt_pk_bf16_f32 v135, v136, v135
	global_store_dwordx2 v[132:133], v[134:135], off offset:288
	s_waitcnt vmcnt(15)
	v_lshlrev_b32_e32 v132, 16, v144
	v_and_b32_e32 v133, 0xffff0000, v144
	v_mul_f32_e32 v132, v44, v132
	v_mul_f32_e32 v133, v45, v133
	v_cvt_pk_bf16_f32 v132, v132, v133
	v_lshlrev_b32_e32 v133, 16, v145
	v_and_b32_e32 v134, 0xffff0000, v145
	v_mul_f32_e32 v133, v46, v133
	v_mul_f32_e32 v134, v47, v134
	v_cvt_pk_bf16_f32 v133, v133, v134
	v_add_u32_e32 v134, s54, v198
	v_ashrrev_i32_e32 v135, 31, v134
	v_lshlrev_b64 v[134:135], 12, v[134:135]
	v_lshl_add_u64 v[134:135], s[4:5], 0, v[134:135]
	v_lshl_add_u64 v[134:135], v[134:135], 0, s[30:31]
	v_lshl_add_u64 v[134:135], v[134:135], 0, s[38:39]
	v_lshl_add_u64 v[134:135], v[134:135], 0, v[128:129]
	global_store_dwordx2 v[134:135], v[132:133], off
	s_waitcnt vmcnt(15)
	v_lshlrev_b32_e32 v132, 16, v146
	v_and_b32_e32 v133, 0xffff0000, v146
	v_mul_f32_e32 v132, v40, v132
	v_mul_f32_e32 v133, v41, v133
	v_cvt_pk_bf16_f32 v132, v132, v133
	v_lshlrev_b32_e32 v133, 16, v147
	v_mul_f32_e32 v133, v42, v133
	v_and_b32_e32 v136, 0xffff0000, v147
	v_mul_f32_e32 v136, v43, v136
	v_cvt_pk_bf16_f32 v133, v133, v136
	global_store_dwordx2 v[134:135], v[132:133], off offset:32
	s_waitcnt vmcnt(15)
	v_lshlrev_b32_e32 v132, 16, v148
	v_and_b32_e32 v133, 0xffff0000, v148
	v_mul_f32_e32 v132, v36, v132
	v_mul_f32_e32 v133, v37, v133
	v_cvt_pk_bf16_f32 v132, v132, v133
	v_lshlrev_b32_e32 v133, 16, v149
	v_mul_f32_e32 v133, v38, v133
	v_and_b32_e32 v136, 0xffff0000, v149
	v_mul_f32_e32 v136, v39, v136
	v_cvt_pk_bf16_f32 v133, v133, v136
	global_store_dwordx2 v[134:135], v[132:133], off offset:256
	s_waitcnt vmcnt(15)
	v_lshlrev_b32_e32 v132, 16, v142
	v_and_b32_e32 v133, 0xffff0000, v142
	v_mul_f32_e32 v132, v32, v132
	v_mul_f32_e32 v133, v33, v133
	v_cvt_pk_bf16_f32 v132, v132, v133
	v_lshlrev_b32_e32 v133, 16, v143
	v_mul_f32_e32 v133, v34, v133
	v_and_b32_e32 v136, 0xffff0000, v143
	v_mul_f32_e32 v136, v35, v136
	v_cvt_pk_bf16_f32 v133, v133, v136
	global_store_dwordx2 v[134:135], v[132:133], off offset:288
	s_waitcnt vmcnt(15)
	v_lshlrev_b32_e32 v132, 16, v152
	v_and_b32_e32 v133, 0xffff0000, v152
	v_mul_f32_e32 v132, v28, v132
	v_mul_f32_e32 v133, v29, v133
	v_cvt_pk_bf16_f32 v132, v132, v133
	v_lshlrev_b32_e32 v133, 16, v153
	v_and_b32_e32 v134, 0xffff0000, v153
	v_mul_f32_e32 v133, v30, v133
	v_mul_f32_e32 v134, v31, v134
	v_cvt_pk_bf16_f32 v133, v133, v134
	v_add_u32_e32 v134, s54, v199
	v_ashrrev_i32_e32 v135, 31, v134
	v_lshlrev_b64 v[134:135], 12, v[134:135]
	v_lshl_add_u64 v[134:135], s[4:5], 0, v[134:135]
	v_lshl_add_u64 v[134:135], v[134:135], 0, s[30:31]
	v_lshl_add_u64 v[134:135], v[134:135], 0, s[38:39]
	v_lshl_add_u64 v[134:135], v[134:135], 0, v[128:129]
	global_store_dwordx2 v[134:135], v[132:133], off
	s_waitcnt vmcnt(15)
	v_lshlrev_b32_e32 v132, 16, v154
	v_and_b32_e32 v133, 0xffff0000, v154
	v_mul_f32_e32 v132, v24, v132
	v_mul_f32_e32 v133, v25, v133
	v_cvt_pk_bf16_f32 v132, v132, v133
	v_lshlrev_b32_e32 v133, 16, v155
	v_mul_f32_e32 v133, v26, v133
	v_and_b32_e32 v136, 0xffff0000, v155
	v_mul_f32_e32 v136, v27, v136
	v_cvt_pk_bf16_f32 v133, v133, v136
	global_store_dwordx2 v[134:135], v[132:133], off offset:32
	s_waitcnt vmcnt(15)
	v_lshlrev_b32_e32 v132, 16, v156
	v_and_b32_e32 v133, 0xffff0000, v156
	v_mul_f32_e32 v132, v20, v132
	v_mul_f32_e32 v133, v21, v133
	v_cvt_pk_bf16_f32 v132, v132, v133
	v_lshlrev_b32_e32 v133, 16, v157
	v_mul_f32_e32 v133, v22, v133
	v_and_b32_e32 v136, 0xffff0000, v157
	v_mul_f32_e32 v136, v23, v136
	v_cvt_pk_bf16_f32 v133, v133, v136
	global_store_dwordx2 v[134:135], v[132:133], off offset:256
	s_waitcnt vmcnt(15)
	v_lshlrev_b32_e32 v132, 16, v150
	v_and_b32_e32 v133, 0xffff0000, v150
	v_mul_f32_e32 v132, v16, v132
	v_mul_f32_e32 v133, v17, v133
	v_cvt_pk_bf16_f32 v132, v132, v133
	v_lshlrev_b32_e32 v133, 16, v151
	v_mul_f32_e32 v133, v18, v133
	v_and_b32_e32 v136, 0xffff0000, v151
	v_mul_f32_e32 v136, v19, v136
	v_cvt_pk_bf16_f32 v133, v133, v136
	global_store_dwordx2 v[134:135], v[132:133], off offset:288
	s_waitcnt vmcnt(15)
	v_lshlrev_b32_e32 v132, 16, v158
	v_and_b32_e32 v133, 0xffff0000, v158
	v_mul_f32_e32 v132, v12, v132
	v_mul_f32_e32 v133, v13, v133
	v_cvt_pk_bf16_f32 v132, v132, v133
	v_lshlrev_b32_e32 v133, 16, v159
	v_and_b32_e32 v134, 0xffff0000, v159
	v_mul_f32_e32 v133, v14, v133
	v_mul_f32_e32 v134, v15, v134
	v_cvt_pk_bf16_f32 v133, v133, v134
	v_add_u32_e32 v134, s54, v200
	v_ashrrev_i32_e32 v135, 31, v134
	v_lshlrev_b64 v[134:135], 12, v[134:135]
	v_lshl_add_u64 v[134:135], s[4:5], 0, v[134:135]
	v_lshl_add_u64 v[134:135], v[134:135], 0, s[30:31]
	v_lshl_add_u64 v[134:135], v[134:135], 0, s[38:39]
	v_lshl_add_u64 v[128:129], v[134:135], 0, v[128:129]
	global_store_dwordx2 v[128:129], v[132:133], off
	s_waitcnt vmcnt(15)
	v_lshlrev_b32_e32 v132, 16, v160
	v_and_b32_e32 v133, 0xffff0000, v160
	v_mul_f32_e32 v132, v8, v132
	v_mul_f32_e32 v133, v9, v133
	v_cvt_pk_bf16_f32 v132, v132, v133
	v_lshlrev_b32_e32 v133, 16, v161
	v_mul_f32_e32 v133, v10, v133
	v_and_b32_e32 v134, 0xffff0000, v161
	v_mul_f32_e32 v134, v11, v134
	v_cvt_pk_bf16_f32 v133, v133, v134
	global_store_dwordx2 v[128:129], v[132:133], off offset:32
	s_waitcnt vmcnt(15)
	v_lshlrev_b32_e32 v132, 16, v162
	v_and_b32_e32 v133, 0xffff0000, v162
	v_mul_f32_e32 v132, v4, v132
	v_mul_f32_e32 v133, v5, v133
	v_cvt_pk_bf16_f32 v132, v132, v133
	v_lshlrev_b32_e32 v133, 16, v163
	v_mul_f32_e32 v133, v6, v133
	v_and_b32_e32 v134, 0xffff0000, v163
	v_mul_f32_e32 v134, v7, v134
	v_cvt_pk_bf16_f32 v133, v133, v134
	global_store_dwordx2 v[128:129], v[132:133], off offset:256
	s_waitcnt vmcnt(15)
	v_lshlrev_b32_e32 v132, 16, v130
	v_and_b32_e32 v130, 0xffff0000, v130
	v_mul_f32_e32 v132, v0, v132
	v_mul_f32_e32 v130, v1, v130
	v_cvt_pk_bf16_f32 v130, v132, v130
	v_lshlrev_b32_e32 v132, 16, v131
	v_and_b32_e32 v131, 0xffff0000, v131
	v_mul_f32_e32 v131, v3, v131
	v_mul_f32_e32 v132, v2, v132
	v_cvt_pk_bf16_f32 v131, v132, v131
	global_store_dwordx2 v[128:129], v[130:131], off offset:288
	s_mov_b64 s[44:45], 0

.LBB0_810:
	s_setprio 0
	s_waitcnt vmcnt(0)
	s_cmpk_gt_u32 s49, 0xff
	s_movk_i32 s74, 0x1fff
	v_readlane_b32 s75, v255, 12
	v_readlane_b32 s53, v255, 49
	s_cbranch_scc1 .LBB0_812
	s_barrier
